# XCD barrier followers poll the global generation word directly (one less release hop per barrier); same generation numbering, own acquire fence kept
# speedup vs baseline: 1.0039x; 1.0039x over previous
.LBB0_572:
	s_or_b64 exec, exec, s[14:15]
	v_cvt_f32_u32_e32 v5, v3
	s_waitcnt vmcnt(0)
	v_readfirstlane_b32 s10, v4
	v_sub_u32_e32 v4, 0, v3
	v_rcp_iflag_f32_e32 v5, v5
	v_add_u32_e32 v6, s10, v0
	v_mul_f32_e32 v5, 0x4f7ffffe, v5
	v_cvt_u32_f32_e32 v5, v5
	v_mul_lo_u32 v0, v4, v5
	v_mul_hi_u32 v0, v5, v0
	v_add_u32_e32 v0, v5, v0
	v_mul_hi_u32 v0, v6, v0
	v_mul_lo_u32 v4, v0, v3
	v_sub_u32_e32 v4, v6, v4
	v_add_u32_e32 v5, 1, v0
	v_cmp_ge_u32_e32 vcc, v4, v3
	s_nop 1
	v_cndmask_b32_e32 v0, v0, v5, vcc
	v_sub_u32_e32 v5, v4, v3
	v_cndmask_b32_e32 v4, v4, v5, vcc
	v_add_u32_e32 v5, 1, v0
	v_cmp_ge_u32_e32 vcc, v4, v3
	v_add_u32_e32 v4, 1, v6
	s_nop 0
	v_cndmask_b32_e32 v0, v0, v5, vcc
	v_mul_lo_u32 v5, v3, v0
	v_add_u32_e32 v3, v5, v3
	v_cmp_ne_u32_e32 vcc, v4, v3
	s_and_saveexec_b64 s[14:15], vcc
	s_xor_b64 s[14:15], exec, s[14:15]
	s_cbranch_execz .LBB0_586
	v_readlane_b32 s16, v255, 12
	v_readlane_b32 s17, v255, 13
	s_waitcnt lgkmcnt(0)
	s_nop 3
	global_load_dword v2, v1, s[16:17] sc1
	s_waitcnt vmcnt(0)
	v_cmp_eq_u32_e32 vcc, v2, v0
	s_and_saveexec_b64 s[16:17], vcc
	s_cbranch_execz .LBB0_585
	s_mov_b32 s10, 1
	s_mov_b64 s[40:41], 0
	s_branch .LBB0_576
